# grid barrier: non-leader workgroups poll the global generation word directly (one hop fewer); XCD leader releases before its own invalidate
# speedup vs baseline: 1.0040x; 1.0011x over previous
.LBB0_139:
	v_readlane_b32 s2, v254, 52
	s_lshl_b32 s88, s2, 6
	s_lshl_b64 s[4:5], s[88:89], 2
	s_add_u32 s4, s28, s4
	s_addc_u32 s5, s29, s5
	v_mov_b32_e32 v0, 0x1000
	v_mov_b32_e32 v4, 1
	global_atomic_add v4, v0, v4, s[4:5] offset:1024 sc0
	v_cvt_f32_u32_e32 v0, v3
	v_sub_u32_e32 v5, 0, v3
	v_rcp_iflag_f32_e32 v0, v0
	s_nop 0
	v_mul_f32_e32 v0, 0x4f7ffffe, v0
	v_cvt_u32_f32_e32 v0, v0
	v_mul_lo_u32 v5, v5, v0
	v_mul_hi_u32 v5, v0, v5
	v_add_u32_e32 v0, v0, v5
	s_waitcnt vmcnt(0)
	v_mul_hi_u32 v0, v4, v0
	v_mul_lo_u32 v5, v0, v3
	v_sub_u32_e32 v5, v4, v5
	v_add_u32_e32 v6, 1, v0
	v_cmp_ge_u32_e32 vcc, v5, v3
	v_add_u32_e32 v4, 1, v4
	s_nop 0
	v_cndmask_b32_e32 v0, v0, v6, vcc
	v_sub_u32_e32 v6, v5, v3
	v_cndmask_b32_e32 v5, v5, v6, vcc
	v_add_u32_e32 v6, 1, v0
	v_cmp_ge_u32_e32 vcc, v5, v3
	s_nop 1
	v_cndmask_b32_e32 v0, v0, v6, vcc
	v_mul_lo_u32 v5, v3, v0
	v_add_u32_e32 v3, v5, v3
	v_cmp_ne_u32_e32 vcc, v4, v3
	s_and_saveexec_b64 s[6:7], vcc
	s_xor_b64 s[6:7], exec, s[6:7]
	s_cbranch_execz .LBB0_153
	s_waitcnt lgkmcnt(0)
	v_readlane_b32 s10, v252, 21
	v_readlane_b32 s11, v252, 22
	s_nop 4
	global_load_dword v2, v1, s[10:11] sc1
	s_waitcnt vmcnt(0)
	v_cmp_eq_u32_e32 vcc, v2, v0
	s_and_saveexec_b64 s[8:9], vcc
	s_cbranch_execz .LBB0_152
	s_mov_b32 s2, 1
	s_mov_b64 s[12:13], 0
	s_branch .LBB0_143

.LBB0_170:
	s_or_b64 exec, exec, s[6:7]
	v_mov_b32_e32 v0, 1
	v_mov_b32_e32 v2, 0x2000
	s_waitcnt vmcnt(0)
	global_atomic_add v2, v0, s[4:5] offset:1024
	buffer_inv sc1
	s_waitcnt vmcnt(0)

.LBB0_303:
	v_readlane_b32 s2, v254, 52
	s_lshl_b32 s88, s2, 6
	s_lshl_b64 s[4:5], s[88:89], 2
	s_add_u32 s6, s28, s4
	s_addc_u32 s7, s29, s5
	v_mov_b32_e32 v0, 0x1000
	v_mov_b32_e32 v4, 1
	global_atomic_add v4, v0, v4, s[6:7] offset:1024 sc0
	v_cvt_f32_u32_e32 v0, v3
	v_sub_u32_e32 v5, 0, v3
	v_rcp_iflag_f32_e32 v0, v0
	s_nop 0
	v_mul_f32_e32 v0, 0x4f7ffffe, v0
	v_cvt_u32_f32_e32 v0, v0
	v_mul_lo_u32 v5, v5, v0
	v_mul_hi_u32 v5, v0, v5
	v_add_u32_e32 v0, v0, v5
	s_waitcnt vmcnt(0)
	v_mul_hi_u32 v0, v4, v0
	v_mul_lo_u32 v5, v0, v3
	v_sub_u32_e32 v5, v4, v5
	v_add_u32_e32 v6, 1, v0
	v_cmp_ge_u32_e32 vcc, v5, v3
	v_add_u32_e32 v4, 1, v4
	s_nop 0
	v_cndmask_b32_e32 v0, v0, v6, vcc
	v_sub_u32_e32 v6, v5, v3
	v_cndmask_b32_e32 v5, v5, v6, vcc
	v_add_u32_e32 v6, 1, v0
	v_cmp_ge_u32_e32 vcc, v5, v3
	s_nop 1
	v_cndmask_b32_e32 v0, v0, v6, vcc
	v_mul_lo_u32 v5, v3, v0
	v_add_u32_e32 v3, v5, v3
	v_cmp_ne_u32_e32 vcc, v4, v3
	s_and_saveexec_b64 s[4:5], vcc
	s_xor_b64 s[4:5], exec, s[4:5]
	s_cbranch_execz .LBB0_317
	s_waitcnt lgkmcnt(0)
	v_readlane_b32 s10, v252, 21
	v_readlane_b32 s11, v252, 22
	s_nop 4
	global_load_dword v2, v1, s[10:11] sc1
	s_waitcnt vmcnt(0)
	v_cmp_eq_u32_e32 vcc, v2, v0
	s_and_saveexec_b64 s[8:9], vcc
	s_cbranch_execz .LBB0_316
	s_mov_b32 s2, 1
	s_mov_b64 s[12:13], 0
	s_branch .LBB0_307

.LBB0_334:
	s_or_b64 exec, exec, s[4:5]
	v_mov_b32_e32 v0, 1
	v_mov_b32_e32 v2, 0x2000
	s_waitcnt vmcnt(0)
	global_atomic_add v2, v0, s[6:7] offset:1024
	buffer_inv sc1
	s_waitcnt vmcnt(0)

.LBB0_1523:
	v_readlane_b32 s2, v254, 52
	s_lshl_b32 s88, s2, 6
	s_lshl_b64 s[4:5], s[88:89], 2
	s_add_u32 s8, s28, s4
	s_addc_u32 s9, s29, s5
	v_mov_b32_e32 v0, 0x1000
	v_mov_b32_e32 v4, 1
	global_atomic_add v4, v0, v4, s[8:9] offset:1024 sc0
	v_cvt_f32_u32_e32 v0, v3
	v_sub_u32_e32 v5, 0, v3
	v_rcp_iflag_f32_e32 v0, v0
	s_nop 0
	v_mul_f32_e32 v0, 0x4f7ffffe, v0
	v_cvt_u32_f32_e32 v0, v0
	v_mul_lo_u32 v5, v5, v0
	v_mul_hi_u32 v5, v0, v5
	v_add_u32_e32 v0, v0, v5
	s_waitcnt vmcnt(0)
	v_mul_hi_u32 v0, v4, v0
	v_mul_lo_u32 v5, v0, v3
	v_sub_u32_e32 v5, v4, v5
	v_add_u32_e32 v6, 1, v0
	v_cmp_ge_u32_e32 vcc, v5, v3
	v_add_u32_e32 v4, 1, v4
	s_nop 0
	v_cndmask_b32_e32 v0, v0, v6, vcc
	v_sub_u32_e32 v6, v5, v3
	v_cndmask_b32_e32 v5, v5, v6, vcc
	v_add_u32_e32 v6, 1, v0
	v_cmp_ge_u32_e32 vcc, v5, v3
	s_nop 1
	v_cndmask_b32_e32 v0, v0, v6, vcc
	v_mul_lo_u32 v5, v3, v0
	v_add_u32_e32 v3, v5, v3
	v_cmp_ne_u32_e32 vcc, v4, v3
	s_and_saveexec_b64 s[4:5], vcc
	s_xor_b64 s[4:5], exec, s[4:5]
	s_cbranch_execz .LBB0_1537
	s_waitcnt lgkmcnt(0)
	v_readlane_b32 s12, v252, 21
	v_readlane_b32 s13, v252, 22
	s_nop 4
	global_load_dword v2, v1, s[12:13] sc1
	s_waitcnt vmcnt(0)
	v_cmp_eq_u32_e32 vcc, v2, v0
	s_and_saveexec_b64 s[10:11], vcc
	s_cbranch_execz .LBB0_1536
	s_mov_b32 s2, 1
	s_mov_b64 s[14:15], 0
	s_branch .LBB0_1527

.LBB0_1554:
	s_or_b64 exec, exec, s[4:5]
	v_mov_b32_e32 v0, 1
	v_mov_b32_e32 v2, 0x2000
	s_waitcnt vmcnt(0)
	global_atomic_add v2, v0, s[8:9] offset:1024
	buffer_inv sc1
	s_waitcnt vmcnt(0)
